# merge-phase stream K loop: first iteration peeled with C=0 MFMAs (no accumulator zeroing); far branch to phase 0 goes through a trampoline
# speedup vs baseline: 1.0131x; 1.0018x over previous
.LBB0_194:
	s_lshr_b32 s16, s14, 6
	s_add_i32 s72, s16, -2
	s_add_u32 s73, s58, 0x100
	s_addc_u32 s75, s59, 0
	s_add_u32 vcc_lo, s68, 0x100
	v_mad_u64_u32 v[0:1], s[18:19], s14, v147, v[146:147]
	s_addc_u32 vcc_hi, s69, 0
	v_mov_b32_e32 v96, v0
	v_mad_u64_u32 v[130:131], s[18:19], s14, v149, v[148:149]
	s_add_u32 s78, s58, 0x80
	v_mov_b32_e32 v131, v97
	s_addc_u32 s79, s59, 0
	s_mov_b32 s76, 0
	s_cmp_eq_u32 s72, s76
	s_cselect_b64 s[18:19], -1, 0
	s_add_i32 s76, s76, 2
	s_and_b64 s[42:43], s[18:19], exec
	s_cselect_b32 s44, s38, s73
	s_cselect_b32 s45, s39, s75
	s_cselect_b32 s47, s61, vcc_hi
	s_cselect_b32 s46, s60, vcc_lo
	s_add_u32 s58, s44, 0x80
	s_addc_u32 s59, s45, 0
	s_add_u32 s42, s46, 0x80
	s_addc_u32 s43, s47, 0
	s_add_i32 s35, 0, 0x10000
	s_and_b64 s[30:31], s[18:19], exec
	s_mov_b64 s[68:69], s[78:79]
	v_add_u32_e32 v144, s35, v170
	s_cselect_b32 s49, s29, s14
	s_add_i32 s70, 0, 0x14000
	ds_read_b128 v[132:135], v144
	ds_read_b128 v[136:139], v144 offset:1024
	ds_read_b128 v[140:143], v144 offset:2048
	ds_read_b128 v[150:153], v144 offset:3072
	v_add_u32_e32 v144, s70, v170
	ds_read_b128 v[154:157], v144
	ds_read_b128 v[158:161], v144 offset:1024
	ds_read_b128 v[162:165], v144 offset:2048
	ds_read_b128 v[172:175], v144 offset:3072
	s_and_b64 s[18:19], s[18:19], exec
	s_cselect_b32 s18, 0, s67
	s_cselect_b32 s19, s20, s66
	s_add_u32 s30, s68, s66
	s_addc_u32 s31, s69, s67
	s_add_i32 m0, s63, 0xc000
	ds_read_b128 v[176:179], v171
	ds_read_b128 v[180:183], v171 offset:1024
	ds_read_b128 v[184:187], v171 offset:2048
	ds_read_b128 v[188:191], v171 offset:3072
	ds_read_b128 v[192:195], v171 offset:4096
	ds_read_b128 v[196:199], v171 offset:5120
	ds_read_b128 v[200:203], v171 offset:6144
	ds_read_b128 v[204:207], v171 offset:7168
	global_load_lds_dwordx4 v96, s[30:31]
	s_add_i32 m0, s63, 0xe000
	s_nop 0
	global_load_lds_dwordx4 v130, s[30:31]
	s_waitcnt vmcnt(8)
	s_waitcnt lgkmcnt(0)
	s_barrier
	s_setprio 1
	s_waitcnt lgkmcnt(0)
	v_mfma_f32_16x16x32_bf16 v[126:129], v[132:135], v[176:179], 0
	v_mfma_f32_16x16x32_bf16 v[122:125], v[140:143], v[176:179], 0
	v_mfma_f32_16x16x32_bf16 v[110:113], v[132:135], v[184:187], 0
	v_mfma_f32_16x16x32_bf16 v[106:109], v[140:143], v[184:187], 0
	v_mfma_f32_16x16x32_bf16 v[92:95], v[132:135], v[192:195], 0
	v_mfma_f32_16x16x32_bf16 v[88:91], v[140:143], v[192:195], 0
	v_mfma_f32_16x16x32_bf16 v[76:79], v[132:135], v[200:203], 0
	v_mfma_f32_16x16x32_bf16 v[72:75], v[140:143], v[200:203], 0
	v_mfma_f32_16x16x32_bf16 v[126:129], v[136:139], v[180:183], v[126:129]
	v_mfma_f32_16x16x32_bf16 v[122:125], v[150:153], v[180:183], v[122:125]
	v_mfma_f32_16x16x32_bf16 v[110:113], v[136:139], v[188:191], v[110:113]
	v_mfma_f32_16x16x32_bf16 v[106:109], v[150:153], v[188:191], v[106:109]
	v_mfma_f32_16x16x32_bf16 v[92:95], v[136:139], v[196:199], v[92:95]
	v_mfma_f32_16x16x32_bf16 v[88:91], v[150:153], v[196:199], v[88:91]
	v_mfma_f32_16x16x32_bf16 v[76:79], v[136:139], v[204:207], v[76:79]
	v_mfma_f32_16x16x32_bf16 v[72:75], v[150:153], v[204:207], v[72:75]
	v_mfma_f32_16x16x32_bf16 v[118:121], v[154:157], v[176:179], 0
	v_mfma_f32_16x16x32_bf16 v[114:117], v[162:165], v[176:179], 0
	v_mfma_f32_16x16x32_bf16 v[102:105], v[154:157], v[184:187], 0
	v_mfma_f32_16x16x32_bf16 v[98:101], v[162:165], v[184:187], 0
	v_mfma_f32_16x16x32_bf16 v[84:87], v[154:157], v[192:195], 0
	v_mfma_f32_16x16x32_bf16 v[80:83], v[162:165], v[192:195], 0
	v_mfma_f32_16x16x32_bf16 v[68:71], v[154:157], v[200:203], 0
	v_mfma_f32_16x16x32_bf16 v[64:67], v[162:165], v[200:203], 0
	v_mfma_f32_16x16x32_bf16 v[118:121], v[158:161], v[180:183], v[118:121]
	v_mfma_f32_16x16x32_bf16 v[114:117], v[172:175], v[180:183], v[114:117]
	v_mfma_f32_16x16x32_bf16 v[102:105], v[158:161], v[188:191], v[102:105]
	v_mfma_f32_16x16x32_bf16 v[98:101], v[172:175], v[188:191], v[98:101]
	v_mfma_f32_16x16x32_bf16 v[84:87], v[158:161], v[196:199], v[84:87]
	v_mfma_f32_16x16x32_bf16 v[80:83], v[172:175], v[196:199], v[80:83]
	v_mfma_f32_16x16x32_bf16 v[68:71], v[158:161], v[204:207], v[68:71]
	v_mfma_f32_16x16x32_bf16 v[64:67], v[172:175], v[204:207], v[64:67]
	s_setprio 0
	s_barrier
	s_add_i32 s35, s35, s80
	v_mad_u64_u32 v[144:145], s[30:31], v168, s49, v[146:147]
	s_mov_b32 m0, s35
	ds_read_b128 v[176:179], v171 offset:16384
	ds_read_b128 v[180:183], v171 offset:17408
	ds_read_b128 v[184:187], v171 offset:18432
	ds_read_b128 v[188:191], v171 offset:19456
	ds_read_b128 v[192:195], v171 offset:20480
	ds_read_b128 v[196:199], v171 offset:21504
	ds_read_b128 v[200:203], v171 offset:22528
	ds_read_b128 v[204:207], v171 offset:23552
	global_load_lds_dwordx4 v144, s[46:47]
	v_mad_u64_u32 v[166:167], s[30:31], v169, s49, v[148:149]
	s_add_i32 m0, s35, 0x2000
	s_add_u32 s30, s46, s19
	s_addc_u32 s31, s47, s18
	s_add_i32 s35, s70, s80
	global_load_lds_dwordx4 v166, s[46:47]
	s_mov_b32 m0, s35
	s_nop 0
	global_load_lds_dwordx4 v144, s[30:31]
	s_add_i32 m0, s35, 0x2000
	s_nop 0
	global_load_lds_dwordx4 v166, s[30:31]
	v_mad_u64_u32 v[208:209], s[30:31], s49, v147, v[146:147]
	s_mov_b32 m0, s63
	v_mad_u64_u32 v[210:211], s[30:31], s49, v149, v[148:149]
	global_load_lds_dwordx4 v208, s[44:45]
	s_mov_b32 m0, s65
	s_nop 0
	global_load_lds_dwordx4 v210, s[44:45]
	s_waitcnt vmcnt(8)
	s_waitcnt lgkmcnt(0)
	s_barrier
	s_setprio 1
	s_waitcnt lgkmcnt(0)
	v_mfma_f32_16x16x32_bf16 v[60:63], v[132:135], v[176:179], 0
	v_mfma_f32_16x16x32_bf16 v[56:59], v[140:143], v[176:179], 0
	v_mfma_f32_16x16x32_bf16 v[44:47], v[132:135], v[184:187], 0
	v_mfma_f32_16x16x32_bf16 v[40:43], v[140:143], v[184:187], 0
	v_mfma_f32_16x16x32_bf16 v[28:31], v[132:135], v[192:195], 0
	v_mfma_f32_16x16x32_bf16 v[24:27], v[140:143], v[192:195], 0
	v_mfma_f32_16x16x32_bf16 v[12:15], v[132:135], v[200:203], 0
	v_mfma_f32_16x16x32_bf16 v[8:11], v[140:143], v[200:203], 0
	v_mfma_f32_16x16x32_bf16 v[60:63], v[136:139], v[180:183], v[60:63]
	v_mfma_f32_16x16x32_bf16 v[56:59], v[150:153], v[180:183], v[56:59]
	v_mfma_f32_16x16x32_bf16 v[44:47], v[136:139], v[188:191], v[44:47]
	v_mfma_f32_16x16x32_bf16 v[40:43], v[150:153], v[188:191], v[40:43]
	v_mfma_f32_16x16x32_bf16 v[28:31], v[136:139], v[196:199], v[28:31]
	v_mfma_f32_16x16x32_bf16 v[24:27], v[150:153], v[196:199], v[24:27]
	v_mfma_f32_16x16x32_bf16 v[12:15], v[136:139], v[204:207], v[12:15]
	v_mfma_f32_16x16x32_bf16 v[8:11], v[150:153], v[204:207], v[8:11]
	v_mfma_f32_16x16x32_bf16 v[52:55], v[154:157], v[176:179], 0
	v_mfma_f32_16x16x32_bf16 v[48:51], v[162:165], v[176:179], 0
	v_mfma_f32_16x16x32_bf16 v[36:39], v[154:157], v[184:187], 0
	v_mfma_f32_16x16x32_bf16 v[32:35], v[162:165], v[184:187], 0
	v_mfma_f32_16x16x32_bf16 v[20:23], v[154:157], v[192:195], 0
	v_mfma_f32_16x16x32_bf16 v[16:19], v[162:165], v[192:195], 0
	v_mfma_f32_16x16x32_bf16 v[4:7], v[154:157], v[200:203], 0
	v_mfma_f32_16x16x32_bf16 v[0:3], v[162:165], v[200:203], 0
	v_mfma_f32_16x16x32_bf16 v[52:55], v[158:161], v[180:183], v[52:55]
	v_mfma_f32_16x16x32_bf16 v[48:51], v[172:175], v[180:183], v[48:51]
	v_mfma_f32_16x16x32_bf16 v[36:39], v[158:161], v[188:191], v[36:39]
	v_mfma_f32_16x16x32_bf16 v[32:35], v[172:175], v[188:191], v[32:35]
	v_mfma_f32_16x16x32_bf16 v[20:23], v[158:161], v[196:199], v[20:23]
	v_mfma_f32_16x16x32_bf16 v[16:19], v[172:175], v[196:199], v[16:19]
	v_mfma_f32_16x16x32_bf16 v[4:7], v[158:161], v[204:207], v[4:7]
	v_mfma_f32_16x16x32_bf16 v[0:3], v[172:175], v[204:207], v[0:3]
	s_setprio 0
	s_barrier
	s_add_i32 s35, 0, 0x18000
	v_add_u32_e32 v145, s35, v170
	s_add_i32 s46, 0, 0x1c000
	ds_read_b128 v[132:135], v145
	ds_read_b128 v[136:139], v145 offset:1024
	ds_read_b128 v[140:143], v145 offset:2048
	ds_read_b128 v[150:153], v145 offset:3072
	v_add_u32_e32 v145, s46, v170
	ds_read_b128 v[154:157], v145
	ds_read_b128 v[158:161], v145 offset:1024
	ds_read_b128 v[162:165], v145 offset:2048
	ds_read_b128 v[172:175], v145 offset:3072
	s_add_u32 s30, s44, s19
	s_addc_u32 s31, s45, s18
	s_mov_b32 m0, s81
	ds_read_b128 v[176:179], v171 offset:32768
	ds_read_b128 v[180:183], v171 offset:33792
	ds_read_b128 v[184:187], v171 offset:34816
	ds_read_b128 v[188:191], v171 offset:35840
	ds_read_b128 v[192:195], v171 offset:36864
	ds_read_b128 v[196:199], v171 offset:37888
	ds_read_b128 v[200:203], v171 offset:38912
	ds_read_b128 v[204:207], v171 offset:39936
	global_load_lds_dwordx4 v208, s[30:31]
	s_mov_b32 m0, s90
	s_nop 0
	global_load_lds_dwordx4 v210, s[30:31]
	s_waitcnt vmcnt(8)
	s_waitcnt lgkmcnt(0)
	s_barrier
	s_setprio 1
	s_waitcnt lgkmcnt(0)
	v_mfma_f32_16x16x32_bf16 v[126:129], v[132:135], v[176:179], v[126:129]
	v_mfma_f32_16x16x32_bf16 v[122:125], v[140:143], v[176:179], v[122:125]
	v_mfma_f32_16x16x32_bf16 v[110:113], v[132:135], v[184:187], v[110:113]
	v_mfma_f32_16x16x32_bf16 v[106:109], v[140:143], v[184:187], v[106:109]
	v_mfma_f32_16x16x32_bf16 v[92:95], v[132:135], v[192:195], v[92:95]
	v_mfma_f32_16x16x32_bf16 v[88:91], v[140:143], v[192:195], v[88:91]
	v_mfma_f32_16x16x32_bf16 v[76:79], v[132:135], v[200:203], v[76:79]
	v_mfma_f32_16x16x32_bf16 v[72:75], v[140:143], v[200:203], v[72:75]
	v_mfma_f32_16x16x32_bf16 v[126:129], v[136:139], v[180:183], v[126:129]
	v_mfma_f32_16x16x32_bf16 v[122:125], v[150:153], v[180:183], v[122:125]
	v_mfma_f32_16x16x32_bf16 v[110:113], v[136:139], v[188:191], v[110:113]
	v_mfma_f32_16x16x32_bf16 v[106:109], v[150:153], v[188:191], v[106:109]
	v_mfma_f32_16x16x32_bf16 v[92:95], v[136:139], v[196:199], v[92:95]
	v_mfma_f32_16x16x32_bf16 v[88:91], v[150:153], v[196:199], v[88:91]
	v_mfma_f32_16x16x32_bf16 v[76:79], v[136:139], v[204:207], v[76:79]
	v_mfma_f32_16x16x32_bf16 v[72:75], v[150:153], v[204:207], v[72:75]
	v_mfma_f32_16x16x32_bf16 v[118:121], v[154:157], v[176:179], v[118:121]
	v_mfma_f32_16x16x32_bf16 v[114:117], v[162:165], v[176:179], v[114:117]
	v_mfma_f32_16x16x32_bf16 v[102:105], v[154:157], v[184:187], v[102:105]
	v_mfma_f32_16x16x32_bf16 v[98:101], v[162:165], v[184:187], v[98:101]
	v_mfma_f32_16x16x32_bf16 v[84:87], v[154:157], v[192:195], v[84:87]
	v_mfma_f32_16x16x32_bf16 v[80:83], v[162:165], v[192:195], v[80:83]
	v_mfma_f32_16x16x32_bf16 v[68:71], v[154:157], v[200:203], v[68:71]
	v_mfma_f32_16x16x32_bf16 v[64:67], v[162:165], v[200:203], v[64:67]
	v_mfma_f32_16x16x32_bf16 v[118:121], v[158:161], v[180:183], v[118:121]
	v_mfma_f32_16x16x32_bf16 v[114:117], v[172:175], v[180:183], v[114:117]
	v_mfma_f32_16x16x32_bf16 v[102:105], v[158:161], v[188:191], v[102:105]
	v_mfma_f32_16x16x32_bf16 v[98:101], v[172:175], v[188:191], v[98:101]
	v_mfma_f32_16x16x32_bf16 v[84:87], v[158:161], v[196:199], v[84:87]
	v_mfma_f32_16x16x32_bf16 v[80:83], v[172:175], v[196:199], v[80:83]
	v_mfma_f32_16x16x32_bf16 v[68:71], v[158:161], v[204:207], v[68:71]
	v_mfma_f32_16x16x32_bf16 v[64:67], v[172:175], v[204:207], v[64:67]
	s_setprio 0
	s_barrier
	s_add_i32 s30, s35, s80
	s_mov_b32 m0, s30
	ds_read_b128 v[176:179], v171 offset:49152
	ds_read_b128 v[180:183], v171 offset:50176
	ds_read_b128 v[184:187], v171 offset:51200
	ds_read_b128 v[188:191], v171 offset:52224
	ds_read_b128 v[192:195], v171 offset:53248
	ds_read_b128 v[196:199], v171 offset:54272
	ds_read_b128 v[200:203], v171 offset:55296
	ds_read_b128 v[204:207], v171 offset:56320
	global_load_lds_dwordx4 v144, s[42:43]
	s_add_i32 m0, s30, 0x2000
	s_add_u32 s30, s42, s19
	s_addc_u32 s31, s43, s18
	s_add_i32 s18, s46, s80
	global_load_lds_dwordx4 v166, s[42:43]
	s_mov_b32 m0, s18
	s_nop 0
	global_load_lds_dwordx4 v144, s[30:31]
	s_add_i32 m0, s18, 0x2000
	s_nop 0
	global_load_lds_dwordx4 v166, s[30:31]
	s_mov_b32 m0, s82
	s_nop 0
	global_load_lds_dwordx4 v208, s[58:59]
	s_mov_b32 m0, s83
	s_nop 0
	global_load_lds_dwordx4 v210, s[58:59]
	s_waitcnt vmcnt(8)
	s_waitcnt lgkmcnt(0)
	s_barrier
	s_setprio 1
	s_waitcnt lgkmcnt(0)
	v_mfma_f32_16x16x32_bf16 v[60:63], v[132:135], v[176:179], v[60:63]
	v_mfma_f32_16x16x32_bf16 v[56:59], v[140:143], v[176:179], v[56:59]
	v_mfma_f32_16x16x32_bf16 v[44:47], v[132:135], v[184:187], v[44:47]
	v_mfma_f32_16x16x32_bf16 v[40:43], v[140:143], v[184:187], v[40:43]
	v_mfma_f32_16x16x32_bf16 v[28:31], v[132:135], v[192:195], v[28:31]
	v_mfma_f32_16x16x32_bf16 v[24:27], v[140:143], v[192:195], v[24:27]
	v_mfma_f32_16x16x32_bf16 v[12:15], v[132:135], v[200:203], v[12:15]
	v_mfma_f32_16x16x32_bf16 v[8:11], v[140:143], v[200:203], v[8:11]
	v_mfma_f32_16x16x32_bf16 v[60:63], v[136:139], v[180:183], v[60:63]
	v_mfma_f32_16x16x32_bf16 v[56:59], v[150:153], v[180:183], v[56:59]
	v_mfma_f32_16x16x32_bf16 v[44:47], v[136:139], v[188:191], v[44:47]
	v_mfma_f32_16x16x32_bf16 v[40:43], v[150:153], v[188:191], v[40:43]
	v_mfma_f32_16x16x32_bf16 v[28:31], v[136:139], v[196:199], v[28:31]
	v_mfma_f32_16x16x32_bf16 v[24:27], v[150:153], v[196:199], v[24:27]
	v_mfma_f32_16x16x32_bf16 v[12:15], v[136:139], v[204:207], v[12:15]
	v_mfma_f32_16x16x32_bf16 v[8:11], v[150:153], v[204:207], v[8:11]
	v_mfma_f32_16x16x32_bf16 v[52:55], v[154:157], v[176:179], v[52:55]
	v_mfma_f32_16x16x32_bf16 v[48:51], v[162:165], v[176:179], v[48:51]
	v_mfma_f32_16x16x32_bf16 v[36:39], v[154:157], v[184:187], v[36:39]
	v_mfma_f32_16x16x32_bf16 v[32:35], v[162:165], v[184:187], v[32:35]
	v_mfma_f32_16x16x32_bf16 v[20:23], v[154:157], v[192:195], v[20:23]
	v_mfma_f32_16x16x32_bf16 v[16:19], v[162:165], v[192:195], v[16:19]
	v_mfma_f32_16x16x32_bf16 v[4:7], v[154:157], v[200:203], v[4:7]
	v_mfma_f32_16x16x32_bf16 v[0:3], v[162:165], v[200:203], v[0:3]
	v_mfma_f32_16x16x32_bf16 v[52:55], v[158:161], v[180:183], v[52:55]
	v_mfma_f32_16x16x32_bf16 v[48:51], v[172:175], v[180:183], v[48:51]
	v_mfma_f32_16x16x32_bf16 v[36:39], v[158:161], v[188:191], v[36:39]
	v_mfma_f32_16x16x32_bf16 v[32:35], v[172:175], v[188:191], v[32:35]
	v_mfma_f32_16x16x32_bf16 v[20:23], v[158:161], v[196:199], v[20:23]
	v_mfma_f32_16x16x32_bf16 v[16:19], v[172:175], v[196:199], v[16:19]
	v_mfma_f32_16x16x32_bf16 v[4:7], v[158:161], v[204:207], v[4:7]
	v_mfma_f32_16x16x32_bf16 v[0:3], v[172:175], v[204:207], v[0:3]
	s_setprio 0
	s_barrier
	s_add_u32 s73, s73, 0x100
	s_addc_u32 s75, s75, 0
	s_add_u32 vcc_lo, vcc_lo, 0x100
	s_addc_u32 vcc_hi, vcc_hi, 0
	s_add_u32 s78, s78, 0x100
	s_addc_u32 s79, s79, 0
	s_cmp_ge_u32 s76, s16
	s_cbranch_scc0 .LBB0_195

.LBB0_387:
	s_and_b64 vcc, exec, s[6:7]
	s_mov_b64 s[6:7], -1
	s_cbranch_vccnz .LBB0_376
	s_branch .LBB0_390
.Ltramp_748:
	s_branch .LBB0_748
.LBB0_388:
	v_lshl_or_b32 v161, v159, 2, s95
	v_lshlrev_b64 v[48:49], 8, v[152:153]
	v_lshlrev_b32_e32 v96, 3, v161
	v_lshl_add_u64 v[48:49], s[58:59], 0, v[48:49]
	v_lshl_add_u64 v[170:171], v[48:49], 0, v[96:97]
	global_load_dwordx4 v[48:51], v[170:171], off offset:16
	s_nop 0
	global_load_dwordx4 v[170:173], v[170:171], off
	s_lshl_b32 s16, s72, 2
	s_add_i32 s16, s96, s16
	s_mul_i32 s18, s16, 0xc0
	s_mov_b32 s19, s21
	s_lshl_b64 s[68:69], s[18:19], 1
	s_waitcnt vmcnt(1)
	v_mov_b32_e32 v176, v48
	s_waitcnt vmcnt(0)
	v_mov_b32_e32 v174, v170
	v_mov_b32_e32 v175, v172
	v_mov_b32_e32 v177, v50
	v_mov_b32_e32 v172, v171
	v_mov_b32_e32 v50, v49
	v_pk_mul_f32 v[174:175], v[168:169], v[174:175] op_sel_hi:[0,1]
	v_pk_mul_f32 v[176:177], v[168:169], v[176:177] op_sel_hi:[0,1]
	v_pk_mul_f32 v[178:179], v[168:169], v[172:173] op_sel_hi:[0,1]
	v_pk_mul_f32 v[48:49], v[168:169], v[50:51] op_sel_hi:[0,1]
	v_mov_b64_e32 v[170:171], s[60:61]
	v_mad_i64_i32 v[50:51], s[22:23], v152, s53, v[170:171]
	v_pk_mul_f32 v[180:181], v[114:115], v[178:179]
	v_pk_mul_f32 v[182:183], v[116:117], v[48:49]
	v_pk_mul_f32 v[184:185], v[114:115], v[174:175]
	v_pk_mul_f32 v[186:187], v[116:117], v[176:177]
	v_lshl_add_u64 v[50:51], v[50:51], 0, s[68:69]
	v_lshlrev_b32_e32 v172, 1, v161
	v_mov_b32_e32 v173, v97
	v_pk_fma_f32 v[182:183], v[124:125], v[176:177], v[182:183] neg_lo:[0,0,1] neg_hi:[0,0,1]
	v_pk_fma_f32 v[180:181], v[122:123], v[174:175], v[180:181] neg_lo:[0,0,1] neg_hi:[0,0,1]
	v_pk_fma_f32 v[186:187], v[124:125], v[48:49], v[186:187]
	v_pk_fma_f32 v[184:185], v[122:123], v[178:179], v[184:185]
	v_lshl_add_u64 v[50:51], v[50:51], 0, v[172:173]
	v_cvt_pk_bf16_f32 v180, v180, v181
	v_cvt_pk_bf16_f32 v181, v182, v183
	v_cvt_pk_bf16_f32 v182, v184, v185
	v_cvt_pk_bf16_f32 v183, v186, v187
	global_store_dwordx2 v[50:51], v[180:181], off offset:256
	global_store_dwordx2 v[50:51], v[182:183], off offset:320
	v_pk_mul_f32 v[180:181], v[118:119], v[178:179]
	v_pk_mul_f32 v[182:183], v[120:121], v[48:49]
	v_pk_fma_f32 v[180:181], v[126:127], v[174:175], v[180:181] neg_lo:[0,0,1] neg_hi:[0,0,1]
	v_pk_fma_f32 v[182:183], v[128:129], v[176:177], v[182:183] neg_lo:[0,0,1] neg_hi:[0,0,1]
	v_pk_mul_f32 v[174:175], v[118:119], v[174:175]
	v_pk_mul_f32 v[176:177], v[120:121], v[176:177]
	v_pk_fma_f32 v[174:175], v[126:127], v[178:179], v[174:175]
	v_pk_fma_f32 v[48:49], v[128:129], v[48:49], v[176:177]
	v_cvt_pk_bf16_f32 v174, v174, v175
	v_cvt_pk_bf16_f32 v175, v48, v49
	v_lshlrev_b64 v[48:49], 8, v[150:151]
	v_cvt_pk_bf16_f32 v176, v180, v181
	v_cvt_pk_bf16_f32 v177, v182, v183
	v_lshl_add_u64 v[48:49], s[58:59], 0, v[48:49]
	global_store_dwordx2 v[50:51], v[176:177], off offset:1024
	global_store_dwordx2 v[50:51], v[174:175], off offset:1088
	v_lshl_add_u64 v[174:175], v[48:49], 0, v[96:97]
	global_load_dwordx4 v[48:51], v[174:175], off offset:16
	s_nop 0
	global_load_dwordx4 v[174:177], v[174:175], off
	s_waitcnt vmcnt(1)
	v_mov_b32_e32 v180, v48
	s_waitcnt vmcnt(0)
	v_mov_b32_e32 v178, v174
	v_mov_b32_e32 v179, v176
	v_mov_b32_e32 v181, v50
	v_mov_b32_e32 v176, v175
	v_mov_b32_e32 v50, v49
	v_pk_mul_f32 v[178:179], v[166:167], v[178:179] op_sel_hi:[0,1]
	v_pk_mul_f32 v[180:181], v[166:167], v[180:181] op_sel_hi:[0,1]
	v_pk_mul_f32 v[174:175], v[166:167], v[176:177] op_sel_hi:[0,1]
	v_pk_mul_f32 v[48:49], v[166:167], v[50:51] op_sel_hi:[0,1]
	v_mad_i64_i32 v[50:51], s[18:19], v150, s53, v[170:171]
	v_pk_mul_f32 v[176:177], v[98:99], v[174:175]
	v_pk_mul_f32 v[182:183], v[100:101], v[48:49]
	v_pk_mul_f32 v[184:185], v[98:99], v[178:179]
	v_pk_mul_f32 v[186:187], v[100:101], v[180:181]
	v_lshl_add_u64 v[50:51], v[50:51], 0, s[68:69]
	v_pk_fma_f32 v[182:183], v[108:109], v[180:181], v[182:183] neg_lo:[0,0,1] neg_hi:[0,0,1]
	v_pk_fma_f32 v[176:177], v[106:107], v[178:179], v[176:177] neg_lo:[0,0,1] neg_hi:[0,0,1]
	v_pk_fma_f32 v[186:187], v[108:109], v[48:49], v[186:187]
	v_pk_fma_f32 v[184:185], v[106:107], v[174:175], v[184:185]
	v_lshl_add_u64 v[50:51], v[50:51], 0, v[172:173]
	v_cvt_pk_bf16_f32 v176, v176, v177
	v_cvt_pk_bf16_f32 v177, v182, v183
	v_cvt_pk_bf16_f32 v182, v184, v185
	v_cvt_pk_bf16_f32 v183, v186, v187
	global_store_dwordx2 v[50:51], v[176:177], off offset:256
	global_store_dwordx2 v[50:51], v[182:183], off offset:320
	v_pk_mul_f32 v[176:177], v[102:103], v[174:175]
	v_pk_mul_f32 v[182:183], v[104:105], v[48:49]
	v_pk_fma_f32 v[176:177], v[110:111], v[178:179], v[176:177] neg_lo:[0,0,1] neg_hi:[0,0,1]
	v_pk_fma_f32 v[182:183], v[112:113], v[180:181], v[182:183] neg_lo:[0,0,1] neg_hi:[0,0,1]
	v_pk_mul_f32 v[178:179], v[102:103], v[178:179]
	v_pk_mul_f32 v[180:181], v[104:105], v[180:181]
	v_pk_fma_f32 v[174:175], v[110:111], v[174:175], v[178:179]
	v_pk_fma_f32 v[48:49], v[112:113], v[48:49], v[180:181]
	v_cvt_pk_bf16_f32 v176, v176, v177
	v_cvt_pk_bf16_f32 v177, v182, v183
	v_cvt_pk_bf16_f32 v174, v174, v175
	v_cvt_pk_bf16_f32 v175, v48, v49
	v_lshlrev_b64 v[48:49], 8, v[148:149]
	global_store_dwordx2 v[50:51], v[176:177], off offset:1024
	global_store_dwordx2 v[50:51], v[174:175], off offset:1088
	v_lshl_add_u64 v[48:49], s[58:59], 0, v[48:49]
	v_lshl_add_u64 v[174:175], v[48:49], 0, v[96:97]
	global_load_dwordx4 v[48:51], v[174:175], off offset:16
	s_nop 0
	global_load_dwordx4 v[174:177], v[174:175], off
	s_waitcnt vmcnt(1)
	v_mov_b32_e32 v180, v48
	s_waitcnt vmcnt(0)
	v_mov_b32_e32 v178, v174
	v_mov_b32_e32 v179, v176
	v_mov_b32_e32 v181, v50
	v_mov_b32_e32 v176, v175
	v_mov_b32_e32 v50, v49
	v_pk_mul_f32 v[178:179], v[164:165], v[178:179] op_sel_hi:[0,1]
	v_pk_mul_f32 v[180:181], v[164:165], v[180:181] op_sel_hi:[0,1]
	v_pk_mul_f32 v[174:175], v[164:165], v[176:177] op_sel_hi:[0,1]
	v_pk_mul_f32 v[48:49], v[164:165], v[50:51] op_sel_hi:[0,1]
	v_mad_i64_i32 v[50:51], s[18:19], v148, s53, v[170:171]
	v_pk_mul_f32 v[176:177], v[80:81], v[174:175]
	v_pk_mul_f32 v[182:183], v[82:83], v[48:49]
	v_pk_mul_f32 v[184:185], v[80:81], v[178:179]
	v_pk_mul_f32 v[186:187], v[82:83], v[180:181]
	v_lshl_add_u64 v[50:51], v[50:51], 0, s[68:69]
	v_pk_fma_f32 v[182:183], v[90:91], v[180:181], v[182:183] neg_lo:[0,0,1] neg_hi:[0,0,1]
	v_pk_fma_f32 v[176:177], v[88:89], v[178:179], v[176:177] neg_lo:[0,0,1] neg_hi:[0,0,1]
	v_pk_fma_f32 v[186:187], v[90:91], v[48:49], v[186:187]
	v_pk_fma_f32 v[184:185], v[88:89], v[174:175], v[184:185]
	v_lshl_add_u64 v[50:51], v[50:51], 0, v[172:173]
	v_cvt_pk_bf16_f32 v176, v176, v177
	v_cvt_pk_bf16_f32 v177, v182, v183
	v_cvt_pk_bf16_f32 v182, v184, v185
	v_cvt_pk_bf16_f32 v183, v186, v187
	global_store_dwordx2 v[50:51], v[176:177], off offset:256
	global_store_dwordx2 v[50:51], v[182:183], off offset:320
	v_pk_mul_f32 v[176:177], v[84:85], v[174:175]
	v_pk_mul_f32 v[182:183], v[86:87], v[48:49]
	v_pk_fma_f32 v[176:177], v[92:93], v[178:179], v[176:177] neg_lo:[0,0,1] neg_hi:[0,0,1]
	v_pk_fma_f32 v[182:183], v[94:95], v[180:181], v[182:183] neg_lo:[0,0,1] neg_hi:[0,0,1]
	v_pk_mul_f32 v[178:179], v[84:85], v[178:179]
	v_pk_mul_f32 v[180:181], v[86:87], v[180:181]
	v_pk_fma_f32 v[174:175], v[92:93], v[174:175], v[178:179]
	v_pk_fma_f32 v[48:49], v[94:95], v[48:49], v[180:181]
	v_cvt_pk_bf16_f32 v174, v174, v175
	v_cvt_pk_bf16_f32 v175, v48, v49
	v_lshlrev_b64 v[48:49], 8, v[146:147]
	v_cvt_pk_bf16_f32 v176, v176, v177
	v_cvt_pk_bf16_f32 v177, v182, v183
	v_lshl_add_u64 v[48:49], s[58:59], 0, v[48:49]
	global_store_dwordx2 v[50:51], v[176:177], off offset:1024
	global_store_dwordx2 v[50:51], v[174:175], off offset:1088
	v_lshl_add_u64 v[174:175], v[48:49], 0, v[96:97]
	global_load_dwordx4 v[48:51], v[174:175], off offset:16
	s_nop 0
	global_load_dwordx4 v[174:177], v[174:175], off
	s_waitcnt vmcnt(1)
	v_mov_b32_e32 v180, v48
	s_waitcnt vmcnt(0)
	v_mov_b32_e32 v178, v174
	v_mov_b32_e32 v179, v176
	v_mov_b32_e32 v181, v50
	v_mov_b32_e32 v176, v175
	v_mov_b32_e32 v50, v49
	v_pk_mul_f32 v[178:179], v[162:163], v[178:179] op_sel_hi:[0,1]
	v_pk_mul_f32 v[180:181], v[162:163], v[180:181] op_sel_hi:[0,1]
	v_pk_mul_f32 v[174:175], v[162:163], v[176:177] op_sel_hi:[0,1]
	v_pk_mul_f32 v[48:49], v[162:163], v[50:51] op_sel_hi:[0,1]
	v_mad_i64_i32 v[50:51], s[18:19], v146, s53, v[170:171]
	v_pk_mul_f32 v[176:177], v[220:221], v[174:175]
	v_pk_mul_f32 v[182:183], v[222:223], v[48:49]
	v_pk_mul_f32 v[184:185], v[220:221], v[178:179]
	v_pk_mul_f32 v[186:187], v[222:223], v[180:181]
	v_lshl_add_u64 v[50:51], v[50:51], 0, s[68:69]
	v_pk_fma_f32 v[182:183], v[58:59], v[180:181], v[182:183] neg_lo:[0,0,1] neg_hi:[0,0,1]
	v_pk_fma_f32 v[176:177], v[56:57], v[178:179], v[176:177] neg_lo:[0,0,1] neg_hi:[0,0,1]
	v_pk_fma_f32 v[186:187], v[58:59], v[48:49], v[186:187]
	v_pk_fma_f32 v[184:185], v[56:57], v[174:175], v[184:185]
	v_lshl_add_u64 v[50:51], v[50:51], 0, v[172:173]
	v_cvt_pk_bf16_f32 v176, v176, v177
	v_cvt_pk_bf16_f32 v177, v182, v183
	v_cvt_pk_bf16_f32 v182, v184, v185
	v_cvt_pk_bf16_f32 v183, v186, v187
	global_store_dwordx2 v[50:51], v[176:177], off offset:256
	global_store_dwordx2 v[50:51], v[182:183], off offset:320
	v_pk_mul_f32 v[176:177], v[52:53], v[174:175]
	v_pk_mul_f32 v[182:183], v[54:55], v[48:49]
	v_pk_fma_f32 v[176:177], v[60:61], v[178:179], v[176:177] neg_lo:[0,0,1] neg_hi:[0,0,1]
	v_pk_fma_f32 v[182:183], v[62:63], v[180:181], v[182:183] neg_lo:[0,0,1] neg_hi:[0,0,1]
	v_pk_mul_f32 v[178:179], v[52:53], v[178:179]
	v_pk_mul_f32 v[180:181], v[54:55], v[180:181]
	v_pk_fma_f32 v[174:175], v[60:61], v[174:175], v[178:179]
	v_pk_fma_f32 v[48:49], v[62:63], v[48:49], v[180:181]
	v_cvt_pk_bf16_f32 v176, v176, v177
	v_cvt_pk_bf16_f32 v177, v182, v183
	v_cvt_pk_bf16_f32 v174, v174, v175
	v_cvt_pk_bf16_f32 v175, v48, v49
	v_lshlrev_b64 v[48:49], 8, v[144:145]
	global_store_dwordx2 v[50:51], v[176:177], off offset:1024
	global_store_dwordx2 v[50:51], v[174:175], off offset:1088
	v_lshl_add_u64 v[48:49], s[58:59], 0, v[48:49]
	v_lshl_add_u64 v[174:175], v[48:49], 0, v[96:97]
	global_load_dwordx4 v[48:51], v[174:175], off offset:16
	s_nop 0
	global_load_dwordx4 v[174:177], v[174:175], off
	s_waitcnt vmcnt(1)
	v_mov_b32_e32 v180, v48
	s_waitcnt vmcnt(0)
	v_mov_b32_e32 v178, v174
	v_mov_b32_e32 v179, v176
	v_mov_b32_e32 v181, v50
	v_mov_b32_e32 v176, v175
	v_mov_b32_e32 v50, v49
	v_pk_mul_f32 v[178:179], v[160:161], v[178:179] op_sel_hi:[0,1]
	v_pk_mul_f32 v[180:181], v[160:161], v[180:181] op_sel_hi:[0,1]
	v_pk_mul_f32 v[174:175], v[160:161], v[176:177] op_sel_hi:[0,1]
	v_pk_mul_f32 v[48:49], v[160:161], v[50:51] op_sel_hi:[0,1]
	v_mad_i64_i32 v[50:51], s[18:19], v144, s53, v[170:171]
	v_pk_mul_f32 v[176:177], v[64:65], v[174:175]
	v_pk_mul_f32 v[182:183], v[66:67], v[48:49]
	v_pk_mul_f32 v[184:185], v[64:65], v[178:179]
	v_pk_mul_f32 v[186:187], v[66:67], v[180:181]
	v_lshl_add_u64 v[50:51], v[50:51], 0, s[68:69]
	v_pk_fma_f32 v[182:183], v[74:75], v[180:181], v[182:183] neg_lo:[0,0,1] neg_hi:[0,0,1]
	v_pk_fma_f32 v[176:177], v[72:73], v[178:179], v[176:177] neg_lo:[0,0,1] neg_hi:[0,0,1]
	v_pk_fma_f32 v[186:187], v[74:75], v[48:49], v[186:187]
	v_pk_fma_f32 v[184:185], v[72:73], v[174:175], v[184:185]
	v_lshl_add_u64 v[50:51], v[50:51], 0, v[172:173]
	v_cvt_pk_bf16_f32 v176, v176, v177
	v_cvt_pk_bf16_f32 v177, v182, v183
	v_cvt_pk_bf16_f32 v182, v184, v185
	v_cvt_pk_bf16_f32 v183, v186, v187
	global_store_dwordx2 v[50:51], v[176:177], off offset:256
	global_store_dwordx2 v[50:51], v[182:183], off offset:320
	v_pk_mul_f32 v[176:177], v[68:69], v[174:175]
	v_pk_mul_f32 v[182:183], v[70:71], v[48:49]
	v_pk_fma_f32 v[176:177], v[76:77], v[178:179], v[176:177] neg_lo:[0,0,1] neg_hi:[0,0,1]
	v_pk_fma_f32 v[182:183], v[78:79], v[180:181], v[182:183] neg_lo:[0,0,1] neg_hi:[0,0,1]
	v_pk_mul_f32 v[178:179], v[68:69], v[178:179]
	v_pk_mul_f32 v[180:181], v[70:71], v[180:181]
	v_pk_fma_f32 v[174:175], v[76:77], v[174:175], v[178:179]
	v_pk_fma_f32 v[48:49], v[78:79], v[48:49], v[180:181]
	v_cvt_pk_bf16_f32 v174, v174, v175
	v_cvt_pk_bf16_f32 v175, v48, v49
	v_lshlrev_b64 v[48:49], 8, v[142:143]
	v_cvt_pk_bf16_f32 v176, v176, v177
	v_cvt_pk_bf16_f32 v177, v182, v183
	v_lshl_add_u64 v[48:49], s[58:59], 0, v[48:49]
	global_store_dwordx2 v[50:51], v[176:177], off offset:1024
	global_store_dwordx2 v[50:51], v[174:175], off offset:1088
	v_lshl_add_u64 v[174:175], v[48:49], 0, v[96:97]
	global_load_dwordx4 v[48:51], v[174:175], off offset:16
	s_nop 0
	global_load_dwordx4 v[174:177], v[174:175], off
	s_waitcnt vmcnt(1)
	v_mov_b32_e32 v180, v48
	s_waitcnt vmcnt(0)
	v_mov_b32_e32 v178, v174
	v_mov_b32_e32 v179, v176
	v_mov_b32_e32 v181, v50
	v_mov_b32_e32 v176, v175
	v_mov_b32_e32 v50, v49
	v_pk_mul_f32 v[178:179], v[158:159], v[178:179] op_sel_hi:[0,1]
	v_pk_mul_f32 v[180:181], v[158:159], v[180:181] op_sel_hi:[0,1]
	v_pk_mul_f32 v[174:175], v[158:159], v[176:177] op_sel_hi:[0,1]
	v_pk_mul_f32 v[48:49], v[158:159], v[50:51] op_sel_hi:[0,1]
	v_mad_i64_i32 v[50:51], s[18:19], v142, s53, v[170:171]
	v_pk_mul_f32 v[176:177], v[32:33], v[174:175]
	v_pk_mul_f32 v[182:183], v[34:35], v[48:49]
	v_pk_mul_f32 v[184:185], v[32:33], v[178:179]
	v_pk_mul_f32 v[186:187], v[34:35], v[180:181]
	v_lshl_add_u64 v[50:51], v[50:51], 0, s[68:69]
	v_pk_fma_f32 v[182:183], v[42:43], v[180:181], v[182:183] neg_lo:[0,0,1] neg_hi:[0,0,1]
	v_pk_fma_f32 v[176:177], v[40:41], v[178:179], v[176:177] neg_lo:[0,0,1] neg_hi:[0,0,1]
	v_pk_fma_f32 v[186:187], v[42:43], v[48:49], v[186:187]
	v_pk_fma_f32 v[184:185], v[40:41], v[174:175], v[184:185]
	v_lshl_add_u64 v[50:51], v[50:51], 0, v[172:173]
	v_cvt_pk_bf16_f32 v176, v176, v177
	v_cvt_pk_bf16_f32 v177, v182, v183
	v_cvt_pk_bf16_f32 v182, v184, v185
	v_cvt_pk_bf16_f32 v183, v186, v187
	global_store_dwordx2 v[50:51], v[176:177], off offset:256
	global_store_dwordx2 v[50:51], v[182:183], off offset:320
	v_pk_mul_f32 v[176:177], v[36:37], v[174:175]
	v_pk_mul_f32 v[182:183], v[38:39], v[48:49]
	v_pk_fma_f32 v[176:177], v[44:45], v[178:179], v[176:177] neg_lo:[0,0,1] neg_hi:[0,0,1]
	v_pk_fma_f32 v[182:183], v[46:47], v[180:181], v[182:183] neg_lo:[0,0,1] neg_hi:[0,0,1]
	v_pk_mul_f32 v[178:179], v[36:37], v[178:179]
	v_pk_mul_f32 v[180:181], v[38:39], v[180:181]
	v_pk_fma_f32 v[174:175], v[44:45], v[174:175], v[178:179]
	v_pk_fma_f32 v[48:49], v[46:47], v[48:49], v[180:181]
	v_cvt_pk_bf16_f32 v176, v176, v177
	v_cvt_pk_bf16_f32 v177, v182, v183
	v_cvt_pk_bf16_f32 v174, v174, v175
	v_cvt_pk_bf16_f32 v175, v48, v49
	v_lshlrev_b64 v[48:49], 8, v[140:141]
	global_store_dwordx2 v[50:51], v[176:177], off offset:1024
	global_store_dwordx2 v[50:51], v[174:175], off offset:1088
	v_lshl_add_u64 v[48:49], s[58:59], 0, v[48:49]
	v_lshl_add_u64 v[174:175], v[48:49], 0, v[96:97]
	global_load_dwordx4 v[48:51], v[174:175], off offset:16
	s_nop 0
	global_load_dwordx4 v[174:177], v[174:175], off
	s_waitcnt vmcnt(1)
	v_mov_b32_e32 v180, v48
	s_waitcnt vmcnt(0)
	v_mov_b32_e32 v178, v174
	v_mov_b32_e32 v179, v176
	v_mov_b32_e32 v181, v50
	v_mov_b32_e32 v176, v175
	v_mov_b32_e32 v50, v49
	v_pk_mul_f32 v[178:179], v[156:157], v[178:179] op_sel_hi:[0,1]
	v_pk_mul_f32 v[180:181], v[156:157], v[180:181] op_sel_hi:[0,1]
	v_pk_mul_f32 v[174:175], v[156:157], v[176:177] op_sel_hi:[0,1]
	v_pk_mul_f32 v[48:49], v[156:157], v[50:51] op_sel_hi:[0,1]
	v_mad_i64_i32 v[50:51], s[18:19], v140, s53, v[170:171]
	v_pk_mul_f32 v[176:177], v[16:17], v[174:175]
	v_pk_mul_f32 v[182:183], v[18:19], v[48:49]
	v_pk_mul_f32 v[184:185], v[16:17], v[178:179]
	v_pk_mul_f32 v[186:187], v[18:19], v[180:181]
	v_lshl_add_u64 v[50:51], v[50:51], 0, s[68:69]
	v_pk_fma_f32 v[182:183], v[26:27], v[180:181], v[182:183] neg_lo:[0,0,1] neg_hi:[0,0,1]
	v_pk_fma_f32 v[176:177], v[24:25], v[178:179], v[176:177] neg_lo:[0,0,1] neg_hi:[0,0,1]
	v_pk_fma_f32 v[186:187], v[26:27], v[48:49], v[186:187]
	v_pk_fma_f32 v[184:185], v[24:25], v[174:175], v[184:185]
	v_lshl_add_u64 v[50:51], v[50:51], 0, v[172:173]
	v_cvt_pk_bf16_f32 v176, v176, v177
	v_cvt_pk_bf16_f32 v177, v182, v183
	v_cvt_pk_bf16_f32 v182, v184, v185
	v_cvt_pk_bf16_f32 v183, v186, v187
	global_store_dwordx2 v[50:51], v[176:177], off offset:256
	global_store_dwordx2 v[50:51], v[182:183], off offset:320
	v_pk_mul_f32 v[176:177], v[20:21], v[174:175]
	v_pk_mul_f32 v[182:183], v[22:23], v[48:49]
	v_pk_fma_f32 v[176:177], v[28:29], v[178:179], v[176:177] neg_lo:[0,0,1] neg_hi:[0,0,1]
	v_pk_fma_f32 v[182:183], v[30:31], v[180:181], v[182:183] neg_lo:[0,0,1] neg_hi:[0,0,1]
	v_pk_mul_f32 v[178:179], v[20:21], v[178:179]
	v_pk_mul_f32 v[180:181], v[22:23], v[180:181]
	v_pk_fma_f32 v[174:175], v[28:29], v[174:175], v[178:179]
	v_pk_fma_f32 v[48:49], v[30:31], v[48:49], v[180:181]
	v_cvt_pk_bf16_f32 v174, v174, v175
	v_cvt_pk_bf16_f32 v175, v48, v49
	v_lshlrev_b64 v[48:49], 8, v[138:139]
	v_cvt_pk_bf16_f32 v176, v176, v177
	v_cvt_pk_bf16_f32 v177, v182, v183
	v_lshl_add_u64 v[48:49], s[58:59], 0, v[48:49]
	global_store_dwordx2 v[50:51], v[176:177], off offset:1024
	global_store_dwordx2 v[50:51], v[174:175], off offset:1088
	v_lshl_add_u64 v[174:175], v[48:49], 0, v[96:97]
	global_load_dwordx4 v[48:51], v[174:175], off offset:16
	s_nop 0
	global_load_dwordx4 v[174:177], v[174:175], off
	s_waitcnt vmcnt(1)
	v_mov_b32_e32 v181, v50
	v_mov_b32_e32 v50, v49
	s_waitcnt vmcnt(0)
	v_mov_b32_e32 v178, v174
	v_mov_b32_e32 v179, v176
	v_mov_b32_e32 v180, v48
	v_mov_b32_e32 v176, v175
	v_pk_mul_f32 v[48:49], v[154:155], v[50:51] op_sel_hi:[0,1]
	v_mad_i64_i32 v[50:51], s[18:19], v138, s53, v[170:171]
	v_pk_mul_f32 v[178:179], v[154:155], v[178:179] op_sel_hi:[0,1]
	v_pk_mul_f32 v[180:181], v[154:155], v[180:181] op_sel_hi:[0,1]
	v_pk_mul_f32 v[174:175], v[154:155], v[176:177] op_sel_hi:[0,1]
	v_lshl_add_u64 v[50:51], v[50:51], 0, s[68:69]
	v_lshl_add_u64 v[50:51], v[50:51], 0, v[172:173]
	v_pk_mul_f32 v[170:171], v[0:1], v[174:175]
	v_pk_mul_f32 v[172:173], v[2:3], v[48:49]
	v_pk_mul_f32 v[176:177], v[0:1], v[178:179]
	v_pk_mul_f32 v[182:183], v[2:3], v[180:181]
	v_pk_fma_f32 v[172:173], v[10:11], v[180:181], v[172:173] neg_lo:[0,0,1] neg_hi:[0,0,1]
	v_pk_fma_f32 v[170:171], v[8:9], v[178:179], v[170:171] neg_lo:[0,0,1] neg_hi:[0,0,1]
	v_pk_fma_f32 v[182:183], v[10:11], v[48:49], v[182:183]
	v_pk_fma_f32 v[176:177], v[8:9], v[174:175], v[176:177]
	v_cvt_pk_bf16_f32 v170, v170, v171
	v_cvt_pk_bf16_f32 v171, v172, v173
	v_cvt_pk_bf16_f32 v172, v176, v177
	v_cvt_pk_bf16_f32 v173, v182, v183
	global_store_dwordx2 v[50:51], v[170:171], off offset:256
	global_store_dwordx2 v[50:51], v[172:173], off offset:320
	v_pk_mul_f32 v[170:171], v[4:5], v[174:175]
	v_pk_mul_f32 v[172:173], v[6:7], v[48:49]
	v_pk_fma_f32 v[170:171], v[12:13], v[178:179], v[170:171] neg_lo:[0,0,1] neg_hi:[0,0,1]
	v_pk_fma_f32 v[172:173], v[14:15], v[180:181], v[172:173] neg_lo:[0,0,1] neg_hi:[0,0,1]
	v_pk_mul_f32 v[176:177], v[4:5], v[178:179]
	v_pk_mul_f32 v[178:179], v[6:7], v[180:181]
	v_pk_fma_f32 v[174:175], v[12:13], v[174:175], v[176:177]
	v_pk_fma_f32 v[48:49], v[14:15], v[48:49], v[178:179]
	v_cvt_pk_bf16_f32 v170, v170, v171
	v_cvt_pk_bf16_f32 v171, v172, v173
	v_cvt_pk_bf16_f32 v172, v174, v175
	v_cvt_pk_bf16_f32 v173, v48, v49
	global_store_dwordx2 v[50:51], v[170:171], off offset:1024
	global_store_dwordx2 v[50:51], v[172:173], off offset:1088
	s_cbranch_execnz .LBB0_387
